# attention: the two register-stage loads before phase A also use the 3-VALU address form
# baseline (speedup 1.0000x reference)
.LBB0_533:
	s_or_b64 exec, exec, s[14:15]
	s_add_i32 s8, s8, s74
	s_lshr_b32 s14, s8, 2
	v_mov_b32_e32 v0, s14
	v_sub_u32_e64 v0, s55, v0 clamp
	s_lshr_b32 s17, s8, 4
	v_readfirstlane_b32 s15, v0
	s_add_i32 s16, s15, 63
	s_lshr_b32 s67, s16, 6
	s_and_b32 s16, s16, 0xc0
	s_add_i32 s16, s16, s14
	v_add_u32_e32 v48, s16, v191
	s_lshl_b32 s98, s52, 7
	s_movk_i32 s99, 0x1ff
	v_add_u32_e32 v250, s98, v184
	v_med3_i32 v2, v48, 0, s99
	v_lshl_add_u32 v2, v2, 9, v250
	global_load_dwordx4 v[4:7], v2, s[10:11]
	global_load_dwordx4 v[12:15], v2, s[12:13]
	v_add_u32_e32 v3, 8, v48
	v_med3_i32 v3, v3, 0, s99
	v_lshl_add_u32 v3, v3, 9, v250
	global_load_dwordx4 v[8:11], v3, s[10:11]
	global_load_dwordx4 v[24:27], v3, s[12:13]
	v_add_u32_e32 v2, 16, v48
	v_med3_i32 v2, v2, 0, s99
	v_lshl_add_u32 v2, v2, 9, v250
	global_load_dwordx4 v[16:19], v2, s[10:11]
	global_load_dwordx4 v[32:35], v2, s[12:13]
	v_add_u32_e32 v3, 24, v48
	v_med3_i32 v3, v3, 0, s99
	v_lshl_add_u32 v3, v3, 9, v250
	global_load_dwordx4 v[20:23], v3, s[10:11]
	global_load_dwordx4 v[40:43], v3, s[12:13]
	v_add_u32_e32 v2, 32, v48
	v_med3_i32 v2, v2, 0, s99
	v_lshl_add_u32 v2, v2, 9, v250
	global_load_dwordx4 v[28:31], v2, s[10:11]
	global_load_dwordx4 v[52:55], v2, s[12:13]
	v_add_u32_e32 v3, 40, v48
	v_med3_i32 v3, v3, 0, s99
	v_lshl_add_u32 v3, v3, 9, v250
	global_load_dwordx4 v[36:39], v3, s[10:11]
	global_load_dwordx4 v[64:67], v3, s[12:13]
	v_add_u32_e32 v2, 48, v48
	v_med3_i32 v2, v2, 0, s99
	v_lshl_add_u32 v2, v2, 9, v250
	global_load_dwordx4 v[44:47], v2, s[10:11]
	global_load_dwordx4 v[76:79], v2, s[12:13]
	v_add_u32_e32 v3, 56, v48
	v_med3_i32 v3, v3, 0, s99
	v_lshl_add_u32 v3, v3, 9, v250
	global_load_dwordx4 v[68:71], v3, s[10:11]
	global_load_dwordx4 v[88:91], v3, s[12:13]
	s_sub_i32 s17, 0x41, s17
	s_max_i32 s17, s17, 0
	s_add_i32 s17, s17, 63
	s_lshr_b32 s66, s17, 6
	s_add_i32 s19, s67, 1
	s_cmpk_lt_u32 s15, 0x41
	s_cselect_b64 s[14:15], -1, 0
	s_and_b64 s[16:17], s[14:15], exec
	s_cselect_b32 s16, 2, 4
	s_cselect_b32 s19, s19, s66
	s_lshr_b32 s20, s8, s16
	s_lshl_b32 s21, s19, 6
	s_lshr_b32 s17, 0x800, s16
	s_add_i32 s21, s21, s20
	s_add_i32 s17, s17, -1
	s_lshl_b32 s33, -1, s16
	s_andn2_b32 s33, s8, s33
	s_lshl_b32 s98, s33, 7
	s_add_i32 s99, s16, 7
	v_add_u32_e32 v251, s21, v191
	v_add_u32_e32 v250, s98, v184
	v_med3_i32 v2, v251, 0, s17
	v_lshl_add_u32 v2, v2, s99, v250
	global_load_dwordx4 v[56:59], v2, s[10:11]
	global_load_dwordx4 v[48:51], v2, s[12:13]
	v_add_u32_e32 v3, 8, v251
	v_med3_i32 v3, v3, 0, s17
	v_lshl_add_u32 v3, v3, s99, v250
	global_load_dwordx4 v[72:75], v3, s[10:11]
	global_load_dwordx4 v[60:63], v3, s[12:13]
	v_add_u32_e32 v2, 16, v251
	v_med3_i32 v2, v2, 0, s17
	v_lshl_add_u32 v2, v2, s99, v250
	global_load_dwordx4 v[84:87], v2, s[10:11]
	global_load_dwordx4 v[80:83], v2, s[12:13]
	v_add_u32_e32 v3, 24, v251
	v_med3_i32 v3, v3, 0, s17
	v_lshl_add_u32 v3, v3, s99, v250
	global_load_dwordx4 v[96:99], v3, s[10:11]
	global_load_dwordx4 v[92:95], v3, s[12:13]
	v_add_u32_e32 v2, 32, v251
	v_med3_i32 v2, v2, 0, s17
	v_lshl_add_u32 v2, v2, s99, v250
	global_load_dwordx4 v[104:107], v2, s[10:11]
	global_load_dwordx4 v[100:103], v2, s[12:13]
	v_add_u32_e32 v3, 40, v251
	v_med3_i32 v3, v3, 0, s17
	v_lshl_add_u32 v3, v3, s99, v250
	global_load_dwordx4 v[112:115], v3, s[10:11]
	global_load_dwordx4 v[108:111], v3, s[12:13]
	v_add_u32_e32 v2, 48, v251
	v_med3_i32 v2, v2, 0, s17
	v_lshl_add_u32 v2, v2, s99, v250
	global_load_dwordx4 v[120:123], v2, s[10:11]
	global_load_dwordx4 v[116:119], v2, s[12:13]
	v_add_u32_e32 v3, 56, v251
	v_med3_i32 v3, v3, 0, s17
	v_lshl_add_u32 v3, v3, s99, v250
	global_load_dwordx4 v[128:131], v3, s[10:11]
	global_load_dwordx4 v[124:127], v3, s[12:13]
	s_cmpk_lt_i32 s18, 0x41
	s_waitcnt lgkmcnt(0)
	s_barrier
	s_cbranch_scc1 .LBB0_535
	v_add_u32_e32 v0, v197, v192
	ds_read_b128 v[140:143], v0
	ds_read_b128 v[144:147], v0 offset:4096
	v_add_u32_e32 v0, v197, v193
	ds_read_b128 v[156:159], v0
	ds_read_b128 v[160:163], v0 offset:4096
	v_add_u32_e32 v2, v197, v194
	ds_read_b128 v[148:151], v2 offset:512
	ds_read_b128 v[152:155], v2 offset:4608
	s_sub_i32 s16, 0x80, s18
	s_waitcnt lgkmcnt(5)
	v_mfma_f32_16x16x32_bf16 v[140:143], v[140:143], v[136:139], 0
	v_add_u32_e32 v2, v197, v195
	v_max_i32_e32 v0, s16, v174
	s_waitcnt lgkmcnt(3)
	v_mfma_f32_16x16x32_bf16 v[140:143], v[156:159], v[132:135], v[140:143]
	ds_read_b128 v[156:159], v2 offset:512
	ds_read_b128 v[164:167], v2 offset:4608
	v_sub_u32_e32 v2, v196, v0
	v_sub_u32_e32 v0, v176, v0
	v_cmp_le_u32_e32 vcc, v0, v2
	s_waitcnt lgkmcnt(3)
	v_mfma_f32_16x16x32_bf16 v[148:151], v[148:151], v[136:139], 0
	s_nop 0
	v_cndmask_b32_e32 v3, v217, v140, vcc
	v_add_u32_e32 v140, 1, v0
	v_cmp_le_u32_e32 vcc, v140, v2
	s_waitcnt lgkmcnt(1)
	v_mfma_f32_16x16x32_bf16 v[148:151], v[156:159], v[132:135], v[148:151]
	v_cndmask_b32_e32 v140, v217, v141, vcc
	v_add_u32_e32 v141, 2, v0
	v_cmp_le_u32_e32 vcc, v141, v2
	v_mfma_f32_16x16x32_bf16 v[144:147], v[144:147], v[136:139], 0
	s_nop 0
	v_cndmask_b32_e32 v141, v217, v142, vcc
	v_add_u32_e32 v142, 3, v0
	v_cmp_le_u32_e32 vcc, v142, v2
	v_mfma_f32_16x16x32_bf16 v[144:147], v[160:163], v[132:135], v[144:147]
	s_nop 0
	v_cndmask_b32_e32 v142, v217, v143, vcc
	v_add_u32_e32 v143, 4, v0
	v_cmp_le_u32_e32 vcc, v143, v2
	v_mfma_f32_16x16x32_bf16 v[152:155], v[152:155], v[136:139], 0
	s_nop 0
	v_cndmask_b32_e32 v143, v217, v148, vcc
	v_add_u32_e32 v148, 5, v0
	v_cmp_le_u32_e32 vcc, v148, v2
	s_waitcnt lgkmcnt(0)
	v_mfma_f32_16x16x32_bf16 v[152:155], v[164:167], v[132:135], v[152:155]
	v_cndmask_b32_e32 v148, v217, v149, vcc
	v_add_u32_e32 v149, 6, v0
	v_cmp_le_u32_e32 vcc, v149, v2
	s_nop 1
	v_cndmask_b32_e32 v149, v217, v150, vcc
	v_add_u32_e32 v150, 7, v0
	v_cmp_le_u32_e32 vcc, v150, v2
	s_nop 1
	v_cndmask_b32_e32 v150, v217, v151, vcc
	v_add_u32_e32 v151, 32, v0
	v_cmp_le_u32_e32 vcc, v151, v2
	v_add_u32_e32 v151, 33, v0
	s_nop 0
	v_cndmask_b32_e32 v144, v217, v144, vcc
	v_cmp_le_u32_e32 vcc, v151, v2
	v_add_u32_e32 v151, 34, v0
	s_nop 0
	v_cndmask_b32_e32 v145, v217, v145, vcc
	v_cmp_le_u32_e32 vcc, v151, v2
	v_add_u32_e32 v151, 35, v0
	s_nop 0
	v_cndmask_b32_e32 v146, v217, v146, vcc
	v_cmp_le_u32_e32 vcc, v151, v2
	v_add_u32_e32 v151, 36, v0
	s_nop 0
	v_cndmask_b32_e32 v147, v217, v147, vcc
	v_cmp_le_u32_e32 vcc, v151, v2
	s_nop 1
	v_cndmask_b32_e32 v151, v217, v152, vcc
	v_add_u32_e32 v152, 37, v0
	v_cmp_le_u32_e32 vcc, v152, v2
	v_add_u32_e32 v152, 38, v0
	v_add_u32_e32 v0, 39, v0
	v_cndmask_b32_e32 v156, v217, v153, vcc
	v_cmp_le_u32_e32 vcc, v152, v2
	v_and_b32_e32 v153, 64, v218
	v_xor_b32_e32 v152, 16, v218
	v_cndmask_b32_e32 v166, v217, v154, vcc
	v_cmp_le_u32_e32 vcc, v0, v2
	v_max3_f32 v2, v3, s62, v140
	v_max3_f32 v2, v2, v141, v142
	v_max3_f32 v2, v2, v143, v148
	v_max3_f32 v2, v2, v149, v150
	v_max3_f32 v2, v2, v144, v145
	v_add_u32_e32 v153, 64, v153
	v_cndmask_b32_e32 v0, v217, v155, vcc
	v_max3_f32 v2, v2, v146, v147
	v_cmp_lt_i32_e32 vcc, v152, v153
	v_max3_f32 v2, v2, v151, v156
	v_max3_f32 v2, v2, v166, v0
	v_cndmask_b32_e32 v152, v218, v152, vcc
	v_lshlrev_b32_e32 v152, 2, v152
	ds_bpermute_b32 v152, v152, v2
	s_waitcnt lgkmcnt(0)
	v_max_f32_e32 v152, v152, v152
	v_max_f32_e32 v2, v2, v152
	v_xor_b32_e32 v152, 32, v218
	v_cmp_lt_i32_e32 vcc, v152, v153
	s_nop 1
	v_cndmask_b32_e32 v152, v218, v152, vcc
	v_lshlrev_b32_e32 v152, 2, v152
	ds_bpermute_b32 v152, v152, v2
	s_waitcnt lgkmcnt(0)
	v_max3_f32 v157, v2, v152, s63
	v_sub_f32_e32 v2, v3, v157
	v_exp_f32_e32 v2, v2
	v_sub_f32_e32 v3, v140, v157
	v_exp_f32_e32 v3, v3
	v_sub_f32_e32 v140, v141, v157
	v_exp_f32_e32 v152, v140
	v_sub_f32_e32 v142, v142, v157
	v_exp_f32_e32 v142, v142
	v_sub_f32_e32 v143, v143, v157
	v_add_f32_e32 v141, 0, v2
	v_exp_f32_e32 v143, v143
	v_sub_f32_e32 v148, v148, v157
	v_add_f32_e32 v141, v3, v141
	v_exp_f32_e32 v148, v148
	v_sub_f32_e32 v149, v149, v157
	v_add_f32_e32 v141, v152, v141
	v_exp_f32_e32 v149, v149
	v_add_f32_e32 v141, v142, v141
	v_add_f32_e32 v141, v143, v141
	v_add_f32_e32 v141, v148, v141
	v_add_f32_e32 v170, v149, v141
	v_sub_f32_e32 v141, v150, v157
	v_exp_f32_e32 v171, v141
	v_sub_f32_e32 v141, v144, v157
	v_sub_f32_e32 v140, 0xe0ad78ec, v157
	v_exp_f32_e32 v186, v141
	v_sub_f32_e32 v141, v145, v157
	v_exp_f32_e32 v187, v141
	v_sub_f32_e32 v141, v146, v157
	v_exp_f32_e32 v231, v140
	v_cvt_pk_bf16_f32 v144, v2, v3
	v_add_u32_e32 v2, s53, v175
	v_exp_f32_e32 v230, v141
	v_sub_f32_e32 v141, v147, v157
	v_sub_f32_e32 v140, v151, v157
	v_cvt_pk_bf16_f32 v145, v152, v142
	v_cvt_pk_bf16_f32 v146, v143, v148
	v_cvt_pk_bf16_f32 v147, v149, v171
	ds_read_b64_tr_b16 v[150:151], v2 offset:50752
	ds_read_b64_tr_b16 v[148:149], v2 offset:50176
	ds_read_b64_tr_b16 v[154:155], v2 offset:50784
	ds_read_b64_tr_b16 v[152:153], v2 offset:50208
	ds_read_b64_tr_b16 v[158:159], v2 offset:50240
	ds_read_b64_tr_b16 v[162:163], v2 offset:50272
	ds_read_b64_tr_b16 v[160:161], v2 offset:50816
	ds_read_b64_tr_b16 v[164:165], v2 offset:50848
	v_exp_f32_e32 v233, v140
	v_mul_f32_e32 v140, 0, v231
	v_exp_f32_e32 v232, v141
	v_mov_b32_e32 v141, v140
	v_mov_b32_e32 v142, v140
	v_mov_b32_e32 v143, v140
	v_sub_f32_e32 v3, v156, v157
	v_sub_f32_e32 v156, v166, v157
	v_sub_f32_e32 v0, v0, v157
	v_add_f32_e32 v170, v171, v170
	s_waitcnt lgkmcnt(6)
	v_mfma_f32_16x16x32_bf16 v[148:151], v[148:151], v[144:147], v[140:143]
	v_exp_f32_e32 v3, v3
	v_exp_f32_e32 v156, v156
	v_exp_f32_e32 v0, v0
	s_waitcnt lgkmcnt(4)
	v_mfma_f32_16x16x32_bf16 v[166:169], v[152:155], v[144:147], v[140:143]
	v_cvt_pk_bf16_f32 v222, v186, v187
	v_cvt_pk_bf16_f32 v223, v230, v232
	v_cvt_pk_bf16_f32 v224, v233, v3
	s_waitcnt lgkmcnt(1)
	v_mfma_f32_16x16x32_bf16 v[158:161], v[158:161], v[144:147], v[140:143]
	v_cvt_pk_bf16_f32 v225, v156, v0
	ds_read_b64_tr_b16 v[154:155], v2 offset:55360
	ds_read_b64_tr_b16 v[152:153], v2 offset:54784
	s_waitcnt lgkmcnt(2)
	v_mfma_f32_16x16x32_bf16 v[140:143], v[162:165], v[144:147], v[140:143]
	ds_read_b64_tr_b16 v[146:147], v2 offset:55392
	ds_read_b64_tr_b16 v[144:145], v2 offset:54816
	ds_read_b64_tr_b16 v[162:163], v2 offset:54848
	ds_read_b64_tr_b16 v[226:227], v2 offset:54880
	ds_read_b64_tr_b16 v[164:165], v2 offset:55424
	ds_read_b64_tr_b16 v[228:229], v2 offset:55456
	v_add_f32_e32 v2, v186, v170
	v_add_f32_e32 v2, v187, v2
	v_add_f32_e32 v2, v230, v2
	v_add_f32_e32 v2, v232, v2
	v_add_f32_e32 v2, v233, v2
	s_waitcnt lgkmcnt(6)
	v_mfma_f32_16x16x32_bf16 v[152:155], v[152:155], v[222:225], v[148:151]
	v_add_f32_e32 v2, v3, v2
	v_add_f32_e32 v2, v156, v2
	s_waitcnt lgkmcnt(0)
	s_waitcnt lgkmcnt(4)
	v_mfma_f32_16x16x32_bf16 v[148:151], v[144:147], v[222:225], v[166:169]
	v_add_f32_e32 v156, v0, v2
	v_fmac_f32_e32 v156, 0, v231
	s_waitcnt lgkmcnt(1)
	v_mfma_f32_16x16x32_bf16 v[144:147], v[162:165], v[222:225], v[158:161]
	s_waitcnt lgkmcnt(0)
	v_mfma_f32_16x16x32_bf16 v[140:143], v[226:229], v[222:225], v[140:143]
	s_cmp_gt_i32 s18, 0
	s_mov_b64 s[16:17], -1
	s_cbranch_scc1 .LBB0_537
	s_branch .LBB0_536
